# prep queue: three-way interleave of filter / adaLN / weight-conversion items
# baseline (speedup 1.0000x reference)
.LBB0_1090:
	s_or_b64 exec, exec, s[10:11]
	s_mov_b64 s[10:11], src_shared_base
	s_cmp_lg_u32 s69, -1
	s_cselect_b32 s3, s69, 0
	s_cselect_b32 s10, s11, 0
	v_mov_b32_e32 v2, s3
	v_mov_b32_e32 v3, s10
	s_waitcnt lgkmcnt(0)
	s_barrier
	flat_load_dword v4, v[2:3] sc0 sc1
	s_waitcnt vmcnt(0)
	s_movk_i32 s3, 0x5b4
	s_mov_b64 s[14:15], -1
	s_waitcnt lgkmcnt(0)
	s_barrier
	v_mov_b32_e32 v2, 0xaaaaaaab
	v_mul_hi_u32 v2, v4, v2
	v_lshrrev_b32_e32 v2, 1, v2
	v_mul_u32_u24_e32 v3, 3, v2
	v_sub_u32_e32 v3, v4, v3
	v_cmp_eq_u32_e32 vcc, 1, v3
	v_add_u32_e32 v250, 0x140, v2
	s_nop 0
	v_cndmask_b32_e32 v250, v2, v250, vcc
	v_cmp_eq_u32_e32 vcc, 2, v3
	v_add_u32_e32 v2, 0x2c0, v2
	s_nop 0
	v_cndmask_b32_e32 v250, v250, v2, vcc
	v_add_u32_e32 v2, 0xfffffec0, v4
	v_cmp_gt_u32_e32 vcc, 0x400, v4
	s_nop 1
	v_cndmask_b32_e32 v2, v4, v2, vcc
	v_cmp_gt_u32_e32 vcc, 0x3c0, v4
	s_nop 1
	v_cndmask_b32_e32 v4, v2, v250, vcc
	v_cmp_gt_i32_e32 vcc, s3, v4
	s_and_saveexec_b64 s[10:11], vcc
	s_cbranch_execz .LBB0_1085
	s_movk_i32 s3, 0x13f
	v_cmp_lt_i32_e32 vcc, s3, v4
	s_and_saveexec_b64 s[12:13], vcc
	s_xor_b64 s[14:15], exec, s[12:13]
	s_cbranch_execz .LBB0_1227
	s_movk_i32 s3, 0x2bf
	v_cmp_lt_u32_e32 vcc, s3, v4
	s_and_saveexec_b64 s[12:13], vcc
	s_xor_b64 s[16:17], exec, s[12:13]
	s_cbranch_execz .LBB0_1220
	s_movk_i32 s3, 0x35f
	v_cmp_lt_u32_e64 s[52:53], s3, v4
	s_movk_i32 s3, 0x364
	v_cmp_gt_u32_e64 s[54:55], s3, v4
	v_cndmask_b32_e64 v0, 0, 1, s[52:53]
	s_movk_i32 s3, 0x3a4
	v_cndmask_b32_e64 v0, 2, v0, s[54:55]
	v_cmp_gt_u32_e64 s[56:57], s3, v4
	s_movk_i32 s3, 0x504
	v_cmp_gt_u32_e32 vcc, s3, v4
	v_cndmask_b32_e64 v0, 3, v0, s[56:57]
	s_nop 0
	v_cndmask_b32_e32 v2, 4, v0, vcc
	v_cmp_lt_i32_e64 s[58:59], 2, v2
	s_and_saveexec_b64 s[12:13], s[58:59]
	s_xor_b64 s[18:19], exec, s[12:13]
	s_cbranch_execz .LBB0_1097
	v_cmp_lt_i32_e64 s[58:59], 3, v2
	s_and_saveexec_b64 s[12:13], s[58:59]
	s_xor_b64 s[20:21], exec, s[12:13]
	s_or_saveexec_b64 s[22:23], s[20:21]
	s_mov_b64 s[20:21], 0
	v_mov_b32_e32 v0, 20
	s_xor_b64 exec, exec, s[22:23]
	s_mov_b64 s[20:21], exec
	v_mov_b32_e32 v0, 16
	s_or_b64 exec, exec, s[22:23]
